# prologue weight transposes: nt (non-temporal) hint on the streaming f32 weight loads
# speedup vs baseline: 1.0056x; 1.0056x over previous
; __device__ __forceinline__ P0Item p0_decode(const Args& a, int it) {
;     ...
;     const int l = it / LAYER_IT; int r = it % LAYER_IT;
;     if (r < IN_IT) { p.W = a.in[1] + (size_t)l * 1024 * INW; p.N = INW; p.WT = (bf16_t*)(ws + WS_WIN) + (size_t)l * INWP * 1024; }
;     else if ((r -= IN_IT) < OUT_IT) { p.W = a.in[6] + (size_t)l * 1024 * 1024; p.N = 1024; p.WT = (bf16_t*)(ws + WS_WOUT) + (size_t)l * 1024 * 1024; }
;     else if ((r -= OUT_IT) < 32 * GU_IT) { const int e = r / GU_IT; r %= GU_IT; p.W = a.in[12] + (size_t)(l * 32 + e) * 1024 * 2048; p.N = 2048; p.WT = (bf16_t*)(ws + WS_WGU + (size_t)(l * 32 + e) * 2048 * 1024); p.mode = 1; }
;     else { r -= 32 * GU_IT; const int e = r / DN_IT; r %= DN_IT; p.W = a.in[14] + (size_t)(l * 32 + e) * 1024 * 1024; p.N = 1024; p.WT = (bf16_t*)(ws + WS_WDN + (size_t)(l * 32 + e) * 1024 * 1024); p.mode = 2; }
;     const int nblk = p.N / 64; p.k0 = (r / nblk) * 64; p.n0 = (r % nblk) * 64;
; __device__ __forceinline__ void phase_prologue(const Args& a, LAS unsigned char* lds, const int tid) {
;     ...
;     if (it < NIT) { const P0Item p = p0_decode(a, it); const float* src = p.W + (size_t)p.k0 * p.N + p.n0 + lane;
; #pragma unroll
;         for (int i = 0; i < 64; ++i) v[i] = src[(size_t)i * p.N]; }
.LBB0_429:
	s_lshr_b32 s22, s12, 6
	v_cvt_f32_i32_e32 v0, s22
	s_sext_i32_i16 s20, s27
	s_waitcnt lgkmcnt(0)
	v_cvt_f32_i32_e32 v1, s20
	s_ashr_i32 s20, s20, 30
	v_rcp_iflag_f32_e32 v2, v0
	s_or_b32 s23, s20, 1
	v_lshlrev_b32_e32 v32, 2, v248
	v_mul_f32_e32 v2, v1, v2
	v_trunc_f32_e32 v2, v2
	v_fma_f32 v1, -v2, v0, v1
	v_cvt_i32_f32_e32 v2, v2
	v_cmp_ge_f32_e64 s[20:21], |v1|, v0
	s_and_b64 s[20:21], s[20:21], exec
	s_cselect_b32 s20, s23, 0
	v_readfirstlane_b32 s21, v2
	s_add_i32 s20, s21, s20
	s_sext_i32_i16 s21, s20
	s_mul_i32 s20, s20, s22
	s_lshl_b32 s22, s21, 6
	s_ashr_i32 s21, s21, 31
	s_sub_i32 s20, s27, s20
	s_mul_i32 s21, s21, s12
	s_mul_hi_u32 s23, s22, s12
	s_sext_i32_i16 s20, s20
	s_add_i32 s23, s23, s21
	s_mul_i32 s22, s22, s12
	s_lshl_b32 s20, s20, 6
	s_lshl_b64 s[22:23], s[22:23], 2
	s_add_u32 s22, s16, s22
	s_addc_u32 s23, s17, s23
	s_ashr_i32 s21, s20, 31
	s_lshl_b64 s[16:17], s[20:21], 2
	s_add_u32 s16, s22, s16
	s_addc_u32 s17, s23, s17
	v_lshl_add_u64 v[0:1], s[16:17], 0, v[32:33]
	s_lshl_b32 s20, s12, 1
	s_mov_b32 s21, s13
	v_lshl_add_u64 v[4:5], s[20:21], 2, v[0:1]
	s_mul_i32 s20, s12, 3
	v_lshl_add_u64 v[6:7], s[20:21], 2, v[0:1]
	s_lshl_b32 s20, s12, 2
	s_waitcnt vmcnt(0)
; __device__ __forceinline__ void phase_prologue(const Args& a, LAS unsigned char* lds, const int tid) {
;     ...
;     if (it < NIT) { const P0Item p = p0_decode(a, it); const float* src = p.W + (size_t)p.k0 * p.N + p.n0 + lane;
; #pragma unroll
;         for (int i = 0; i < 64; ++i) v[i] = src[(size_t)i * p.N]; }
	v_lshl_add_u64 v[12:13], s[20:21], 2, v[0:1]
	s_mul_i32 s20, s12, 5
	v_lshl_add_u64 v[14:15], s[20:21], 2, v[0:1]
	s_mul_i32 s20, s12, 6
	v_lshl_add_u64 v[16:17], s[20:21], 2, v[0:1]
	s_mul_i32 s20, s12, 7
	v_lshl_add_u64 v[18:19], s[20:21], 2, v[0:1]
	s_lshl_b32 s20, s12, 3
	v_lshl_add_u64 v[2:3], s[12:13], 2, v[0:1]
	v_lshl_add_u64 v[20:21], s[20:21], 2, v[0:1]
	s_mul_i32 s20, s12, 9
	global_load_dword v8, v[2:3], off nt
	global_load_dword v9, v[4:5], off nt
	global_load_dword v10, v[6:7], off nt
	global_load_dword v11, v[12:13], off nt
	s_nop 0
	global_load_dword v12, v[14:15], off nt
	global_load_dword v13, v[16:17], off nt
	s_nop 0
	global_load_dword v14, v[18:19], off nt
	global_load_dword v15, v[20:21], off nt
	v_lshl_add_u64 v[2:3], s[20:21], 2, v[0:1]
	s_mul_i32 s20, s12, 10
	v_lshl_add_u64 v[4:5], s[20:21], 2, v[0:1]
	s_mul_i32 s20, s12, 11
	v_lshl_add_u64 v[6:7], s[20:21], 2, v[0:1]
	s_mul_i32 s20, s12, 12
	v_lshl_add_u64 v[20:21], s[20:21], 2, v[0:1]
	s_mul_i32 s20, s12, 13
	v_lshl_add_u64 v[22:23], s[20:21], 2, v[0:1]
	s_mul_i32 s20, s12, 14
	v_lshl_add_u64 v[24:25], s[20:21], 2, v[0:1]
	s_mul_i32 s20, s12, 15
	v_lshl_add_u64 v[26:27], s[20:21], 2, v[0:1]
	s_lshl_b32 s20, s12, 4
	v_lshl_add_u64 v[28:29], s[20:21], 2, v[0:1]
	s_mul_i32 s20, s12, 17
	global_load_dword v16, v[2:3], off nt
	global_load_dword v17, v[4:5], off nt
	global_load_dword v18, v[6:7], off nt
	global_load_dword v19, v[20:21], off nt
	s_nop 0
	global_load_dword v20, v[22:23], off nt
	global_load_dword v21, v[24:25], off nt
	s_nop 0
	global_load_dword v22, v[26:27], off nt
	global_load_dword v23, v[28:29], off nt
	v_lshl_add_u64 v[2:3], s[20:21], 2, v[0:1]
	s_mul_i32 s20, s12, 18
	v_lshl_add_u64 v[4:5], s[20:21], 2, v[0:1]
	s_mul_i32 s20, s12, 19
	v_lshl_add_u64 v[6:7], s[20:21], 2, v[0:1]
	s_mul_i32 s20, s12, 20
	v_lshl_add_u64 v[28:29], s[20:21], 2, v[0:1]
	s_mul_i32 s20, s12, 21
	v_lshl_add_u64 v[30:31], s[20:21], 2, v[0:1]
	s_mul_i32 s20, s12, 22
	v_lshl_add_u64 v[34:35], s[20:21], 2, v[0:1]
	s_mul_i32 s20, s12, 23
	v_lshl_add_u64 v[36:37], s[20:21], 2, v[0:1]
	s_mul_i32 s20, s12, 24
	v_lshl_add_u64 v[40:41], s[20:21], 2, v[0:1]
	s_mul_i32 s20, s12, 25
	global_load_dword v24, v[2:3], off nt
	global_load_dword v25, v[4:5], off nt
	global_load_dword v26, v[6:7], off nt
	global_load_dword v27, v[28:29], off nt
	s_nop 0
	global_load_dword v28, v[30:31], off nt
	global_load_dword v29, v[34:35], off nt
	s_nop 0
	global_load_dword v30, v[36:37], off nt
	global_load_dword v31, v[40:41], off nt
	v_lshl_add_u64 v[2:3], s[20:21], 2, v[0:1]
	s_mul_i32 s20, s12, 26
	v_lshl_add_u64 v[4:5], s[20:21], 2, v[0:1]
	s_mul_i32 s20, s12, 27
	v_lshl_add_u64 v[6:7], s[20:21], 2, v[0:1]
	s_mul_i32 s20, s12, 28
	v_lshl_add_u64 v[34:35], s[20:21], 2, v[0:1]
	s_mul_i32 s20, s12, 29
	v_lshl_add_u64 v[36:37], s[20:21], 2, v[0:1]
	s_mul_i32 s20, s12, 30
	v_lshl_add_u64 v[40:41], s[20:21], 2, v[0:1]
	s_mul_i32 s20, s12, 31
	v_lshl_add_u64 v[42:43], s[20:21], 2, v[0:1]
	s_lshl_b32 s20, s12, 5
	v_lshl_add_u64 v[44:45], s[20:21], 2, v[0:1]
	s_mul_i32 s20, s12, 33
	global_load_dword v48, v[2:3], off nt
	global_load_dword v49, v[4:5], off nt
	global_load_dword v50, v[6:7], off nt
	global_load_dword v51, v[34:35], off nt
	global_load_dword v52, v[36:37], off nt
	global_load_dword v53, v[40:41], off nt
	global_load_dword v54, v[42:43], off nt
	global_load_dword v55, v[44:45], off nt
	v_lshl_add_u64 v[2:3], s[20:21], 2, v[0:1]
	s_mul_i32 s20, s12, 34
	v_lshl_add_u64 v[4:5], s[20:21], 2, v[0:1]
	s_mul_i32 s20, s12, 35
	v_lshl_add_u64 v[6:7], s[20:21], 2, v[0:1]
	s_mul_i32 s20, s12, 36
	v_lshl_add_u64 v[34:35], s[20:21], 2, v[0:1]
	s_mul_i32 s20, s12, 37
	v_lshl_add_u64 v[36:37], s[20:21], 2, v[0:1]
	s_mul_i32 s20, s12, 38
	v_lshl_add_u64 v[40:41], s[20:21], 2, v[0:1]
	s_mul_i32 s20, s12, 39
	v_lshl_add_u64 v[42:43], s[20:21], 2, v[0:1]
	s_mul_i32 s20, s12, 40
	v_lshl_add_u64 v[44:45], s[20:21], 2, v[0:1]
	s_mul_i32 s20, s12, 41
	global_load_dword v56, v[2:3], off nt
	global_load_dword v57, v[4:5], off nt
	global_load_dword v58, v[6:7], off nt
	global_load_dword v59, v[34:35], off nt
	global_load_dword v60, v[36:37], off nt
	global_load_dword v61, v[40:41], off nt
	global_load_dword v62, v[42:43], off nt
	global_load_dword v63, v[44:45], off nt
	v_lshl_add_u64 v[2:3], s[20:21], 2, v[0:1]
	s_mul_i32 s20, s12, 42
	v_lshl_add_u64 v[4:5], s[20:21], 2, v[0:1]
	s_mul_i32 s20, s12, 43
	v_lshl_add_u64 v[6:7], s[20:21], 2, v[0:1]
	s_mul_i32 s20, s12, 44
	v_lshl_add_u64 v[34:35], s[20:21], 2, v[0:1]
	s_mul_i32 s20, s12, 45
	v_lshl_add_u64 v[36:37], s[20:21], 2, v[0:1]
	s_mul_i32 s20, s12, 46
	v_lshl_add_u64 v[40:41], s[20:21], 2, v[0:1]
	s_mul_i32 s20, s12, 47
	v_lshl_add_u64 v[42:43], s[20:21], 2, v[0:1]
	s_mul_i32 s20, s12, 48
	v_lshl_add_u64 v[44:45], s[20:21], 2, v[0:1]
	s_mul_i32 s20, s12, 49
	global_load_dword v64, v[2:3], off nt
	global_load_dword v65, v[4:5], off nt
	global_load_dword v66, v[6:7], off nt
	global_load_dword v67, v[34:35], off nt
	global_load_dword v68, v[36:37], off nt
	global_load_dword v69, v[40:41], off nt
	global_load_dword v70, v[42:43], off nt
	global_load_dword v71, v[44:45], off nt
	v_lshl_add_u64 v[2:3], s[20:21], 2, v[0:1]
	s_mul_i32 s20, s12, 50
	v_lshl_add_u64 v[4:5], s[20:21], 2, v[0:1]
	s_mul_i32 s20, s12, 51
	v_lshl_add_u64 v[6:7], s[20:21], 2, v[0:1]
	s_mul_i32 s20, s12, 52
	v_lshl_add_u64 v[34:35], s[20:21], 2, v[0:1]
	s_mul_i32 s20, s12, 53
	v_lshl_add_u64 v[36:37], s[20:21], 2, v[0:1]
	s_mul_i32 s20, s12, 54
	v_lshl_add_u64 v[40:41], s[20:21], 2, v[0:1]
	s_mul_i32 s20, s12, 55
	v_lshl_add_u64 v[42:43], s[20:21], 2, v[0:1]
	s_mul_i32 s20, s12, 56
	v_lshl_add_u64 v[44:45], s[20:21], 2, v[0:1]
	s_mul_i32 s20, s12, 57
	global_load_dword v72, v[2:3], off nt
	global_load_dword v73, v[4:5], off nt
	global_load_dword v74, v[6:7], off nt
	global_load_dword v75, v[34:35], off nt
	global_load_dword v76, v[36:37], off nt
	global_load_dword v77, v[40:41], off nt
	global_load_dword v78, v[42:43], off nt
	global_load_dword v79, v[44:45], off nt
	v_lshl_add_u64 v[2:3], s[20:21], 2, v[0:1]
	s_mul_i32 s20, s12, 58
	v_lshl_add_u64 v[4:5], s[20:21], 2, v[0:1]
	s_mul_i32 s20, s12, 59
	v_lshl_add_u64 v[6:7], s[20:21], 2, v[0:1]
	s_mul_i32 s20, s12, 60
	v_lshl_add_u64 v[34:35], s[20:21], 2, v[0:1]
	s_mul_i32 s20, s12, 61
	v_lshl_add_u64 v[36:37], s[20:21], 2, v[0:1]
	s_mul_i32 s20, s12, 62
	s_mul_i32 s12, s12, 63
	v_lshl_add_u64 v[40:41], s[20:21], 2, v[0:1]
	v_lshl_add_u64 v[0:1], s[12:13], 2, v[0:1]
	global_load_dword v80, v32, s[16:17]
	global_load_dword v81, v[2:3], off nt
	global_load_dword v82, v[4:5], off nt
	global_load_dword v83, v[6:7], off nt
	global_load_dword v84, v[34:35], off nt
	global_load_dword v85, v[36:37], off nt
	global_load_dword v86, v[40:41], off nt
	global_load_dword v87, v[0:1], off nt

; __device__ __forceinline__ P0Item p0_decode(const Args& a, int it) {
;     ...
;     const int l = it / LAYER_IT; int r = it % LAYER_IT;
;     if (r < IN_IT) { p.W = a.in[1] + (size_t)l * 1024 * INW; p.N = INW; p.WT = (bf16_t*)(ws + WS_WIN) + (size_t)l * INWP * 1024; }
;     else if ((r -= IN_IT) < OUT_IT) { p.W = a.in[6] + (size_t)l * 1024 * 1024; p.N = 1024; p.WT = (bf16_t*)(ws + WS_WOUT) + (size_t)l * 1024 * 1024; }
;     else if ((r -= OUT_IT) < 32 * GU_IT) { const int e = r / GU_IT; r %= GU_IT; p.W = a.in[12] + (size_t)(l * 32 + e) * 1024 * 2048; p.N = 2048; p.WT = (bf16_t*)(ws + WS_WGU + (size_t)(l * 32 + e) * 2048 * 1024); p.mode = 1; }
;     else { r -= 32 * GU_IT; const int e = r / DN_IT; r %= DN_IT; p.W = a.in[14] + (size_t)(l * 32 + e) * 1024 * 1024; p.N = 1024; p.WT = (bf16_t*)(ws + WS_WDN + (size_t)(l * 32 + e) * 1024 * 1024); p.mode = 2; }
;     const int nblk = p.N / 64; p.k0 = (r / nblk) * 64; p.n0 = (r % nblk) * 64;
; __device__ __forceinline__ void phase_prologue(const Args& a, LAS unsigned char* lds, const int tid) {
;     ...
;         if (it + NGW < NIT) { const P0Item pn = p0_decode(a, it + NGW); const float* src = pn.W + (size_t)pn.k0 * pn.N + pn.n0 + lane;
; #pragma unroll
;             for (int i = 0; i < 64; ++i) v[i] = src[(size_t)i * pn.N]; }
.LBB0_456:
	s_lshr_b32 s38, s12, 6
	v_cvt_f32_i32_e32 v4, s38
	s_sext_i32_i16 s36, s45
	v_cvt_f32_i32_e32 v5, s36
	s_ashr_i32 s36, s36, 30
	v_rcp_iflag_f32_e32 v6, v4
	s_or_b32 s39, s36, 1
	v_mul_f32_e32 v6, v5, v6
	v_trunc_f32_e32 v6, v6
	v_fma_f32 v5, -v6, v4, v5
	v_cvt_i32_f32_e32 v6, v6
	v_cmp_ge_f32_e64 s[36:37], |v5|, v4
	s_and_b64 s[36:37], s[36:37], exec
	s_cselect_b32 s36, s39, 0
	v_readfirstlane_b32 s37, v6
	s_add_i32 s36, s37, s36
	s_sext_i32_i16 s37, s36
	s_mul_i32 s36, s36, s38
	s_lshl_b32 s38, s37, 6
	s_ashr_i32 s37, s37, 31
	s_sub_i32 s36, s45, s36
	s_mul_i32 s37, s37, s12
	s_mul_hi_u32 s39, s38, s12
	s_sext_i32_i16 s36, s36
	s_add_i32 s39, s39, s37
	s_mul_i32 s38, s38, s12
	s_lshl_b32 s36, s36, 6
	s_lshl_b64 s[38:39], s[38:39], 2
	s_add_u32 s38, s26, s38
	s_addc_u32 s39, s27, s39
	s_ashr_i32 s37, s36, 31
	s_lshl_b64 s[26:27], s[36:37], 2
	s_add_u32 s26, s38, s26
	s_addc_u32 s27, s39, s27
	v_lshl_add_u64 v[4:5], s[26:27], 0, v[32:33]
	s_lshl_b32 s36, s12, 1
	s_mov_b32 s37, s13
	v_lshl_add_u64 v[10:11], s[36:37], 2, v[4:5]
	s_mul_i32 s36, s12, 3
	v_lshl_add_u64 v[12:13], s[36:37], 2, v[4:5]
	s_lshl_b32 s36, s12, 2
	v_lshl_add_u64 v[14:15], s[36:37], 2, v[4:5]
	s_mul_i32 s36, s12, 5
	v_lshl_add_u64 v[16:17], s[36:37], 2, v[4:5]
	s_mul_i32 s36, s12, 6
	v_lshl_add_u64 v[18:19], s[36:37], 2, v[4:5]
	s_mul_i32 s36, s12, 7
	v_lshl_add_u64 v[20:21], s[36:37], 2, v[4:5]
	s_lshl_b32 s36, s12, 3
	v_lshl_add_u64 v[6:7], s[12:13], 2, v[4:5]
	v_lshl_add_u64 v[22:23], s[36:37], 2, v[4:5]
	s_mul_i32 s36, s12, 9
	global_load_dword v8, v[6:7], off nt
	global_load_dword v9, v[10:11], off nt
	s_nop 0
	global_load_dword v10, v[12:13], off nt
	global_load_dword v11, v[14:15], off nt
	s_nop 0
	global_load_dword v12, v[16:17], off nt
	global_load_dword v13, v[18:19], off nt
	global_load_dword v14, v[20:21], off nt
	global_load_dword v15, v[22:23], off nt
	v_lshl_add_u64 v[6:7], s[36:37], 2, v[4:5]
	s_mul_i32 s36, s12, 10
	v_lshl_add_u64 v[18:19], s[36:37], 2, v[4:5]
	s_mul_i32 s36, s12, 11
	v_lshl_add_u64 v[20:21], s[36:37], 2, v[4:5]
	s_mul_i32 s36, s12, 12
	v_lshl_add_u64 v[22:23], s[36:37], 2, v[4:5]
	s_mul_i32 s36, s12, 13
	v_lshl_add_u64 v[24:25], s[36:37], 2, v[4:5]
	s_mul_i32 s36, s12, 14
	v_lshl_add_u64 v[26:27], s[36:37], 2, v[4:5]
	s_mul_i32 s36, s12, 15
	v_lshl_add_u64 v[28:29], s[36:37], 2, v[4:5]
	s_lshl_b32 s36, s12, 4
	v_lshl_add_u64 v[30:31], s[36:37], 2, v[4:5]
	s_mul_i32 s36, s12, 17
	global_load_dword v16, v[6:7], off nt
	global_load_dword v17, v[18:19], off nt
	s_nop 0
	global_load_dword v18, v[20:21], off nt
	global_load_dword v19, v[22:23], off nt
	s_nop 0
	global_load_dword v20, v[24:25], off nt
	global_load_dword v21, v[26:27], off nt
	global_load_dword v22, v[28:29], off nt
	global_load_dword v23, v[30:31], off nt
	v_lshl_add_u64 v[6:7], s[36:37], 2, v[4:5]
	s_mul_i32 s36, s12, 18
	v_lshl_add_u64 v[26:27], s[36:37], 2, v[4:5]
	s_mul_i32 s36, s12, 19
	v_lshl_add_u64 v[28:29], s[36:37], 2, v[4:5]
	s_mul_i32 s36, s12, 20
	v_lshl_add_u64 v[30:31], s[36:37], 2, v[4:5]
	s_mul_i32 s36, s12, 21
	v_lshl_add_u64 v[48:49], s[36:37], 2, v[4:5]
	s_mul_i32 s36, s12, 22
	v_lshl_add_u64 v[50:51], s[36:37], 2, v[4:5]
	s_mul_i32 s36, s12, 23
	v_lshl_add_u64 v[52:53], s[36:37], 2, v[4:5]
	s_mul_i32 s36, s12, 24
	v_lshl_add_u64 v[54:55], s[36:37], 2, v[4:5]
	s_mul_i32 s36, s12, 25
	global_load_dword v24, v[6:7], off nt
	global_load_dword v25, v[26:27], off nt
	s_nop 0
	global_load_dword v26, v[28:29], off nt
	global_load_dword v27, v[30:31], off nt
	s_nop 0
	global_load_dword v28, v[48:49], off nt
	global_load_dword v29, v[50:51], off nt
	global_load_dword v30, v[52:53], off nt
	global_load_dword v31, v[54:55], off nt
	v_lshl_add_u64 v[6:7], s[36:37], 2, v[4:5]
	s_mul_i32 s36, s12, 26
	v_lshl_add_u64 v[50:51], s[36:37], 2, v[4:5]
	s_mul_i32 s36, s12, 27
	v_lshl_add_u64 v[52:53], s[36:37], 2, v[4:5]
	s_mul_i32 s36, s12, 28
	v_lshl_add_u64 v[54:55], s[36:37], 2, v[4:5]
	s_mul_i32 s36, s12, 29
	v_lshl_add_u64 v[56:57], s[36:37], 2, v[4:5]
	s_mul_i32 s36, s12, 30
	v_lshl_add_u64 v[58:59], s[36:37], 2, v[4:5]
; __device__ __forceinline__ void phase_prologue(const Args& a, LAS unsigned char* lds, const int tid) {
;     ...
;         if (it + NGW < NIT) { const P0Item pn = p0_decode(a, it + NGW); const float* src = pn.W + (size_t)pn.k0 * pn.N + pn.n0 + lane;
; #pragma unroll
;             for (int i = 0; i < 64; ++i) v[i] = src[(size_t)i * pn.N]; }
	s_mul_i32 s36, s12, 31
	v_lshl_add_u64 v[60:61], s[36:37], 2, v[4:5]
	s_lshl_b32 s36, s12, 5
	v_lshl_add_u64 v[62:63], s[36:37], 2, v[4:5]
	s_mul_i32 s36, s12, 33
	global_load_dword v48, v[6:7], off nt
	global_load_dword v49, v[50:51], off nt
	s_nop 0
	global_load_dword v50, v[52:53], off nt
	global_load_dword v51, v[54:55], off nt
	s_nop 0
	global_load_dword v52, v[56:57], off nt
	global_load_dword v53, v[58:59], off nt
	global_load_dword v54, v[60:61], off nt
	global_load_dword v55, v[62:63], off nt
	v_lshl_add_u64 v[6:7], s[36:37], 2, v[4:5]
	s_mul_i32 s36, s12, 34
	v_lshl_add_u64 v[58:59], s[36:37], 2, v[4:5]
	s_mul_i32 s36, s12, 35
	v_lshl_add_u64 v[60:61], s[36:37], 2, v[4:5]
	s_mul_i32 s36, s12, 36
	v_lshl_add_u64 v[62:63], s[36:37], 2, v[4:5]
	s_mul_i32 s36, s12, 37
	v_lshl_add_u64 v[64:65], s[36:37], 2, v[4:5]
	s_mul_i32 s36, s12, 38
	v_lshl_add_u64 v[66:67], s[36:37], 2, v[4:5]
	s_mul_i32 s36, s12, 39
	v_lshl_add_u64 v[68:69], s[36:37], 2, v[4:5]
	s_mul_i32 s36, s12, 40
	v_lshl_add_u64 v[70:71], s[36:37], 2, v[4:5]
	s_mul_i32 s36, s12, 41
	global_load_dword v56, v[6:7], off nt
	global_load_dword v57, v[58:59], off nt
	s_nop 0
	global_load_dword v58, v[60:61], off nt
	global_load_dword v59, v[62:63], off nt
	s_nop 0
	global_load_dword v60, v[64:65], off nt
	global_load_dword v61, v[66:67], off nt
	global_load_dword v62, v[68:69], off nt
	global_load_dword v63, v[70:71], off nt
	v_lshl_add_u64 v[6:7], s[36:37], 2, v[4:5]
	s_mul_i32 s36, s12, 42
	v_lshl_add_u64 v[66:67], s[36:37], 2, v[4:5]
	s_mul_i32 s36, s12, 43
	v_lshl_add_u64 v[68:69], s[36:37], 2, v[4:5]
	s_mul_i32 s36, s12, 44
	v_lshl_add_u64 v[70:71], s[36:37], 2, v[4:5]
	s_mul_i32 s36, s12, 45
	v_lshl_add_u64 v[72:73], s[36:37], 2, v[4:5]
	s_mul_i32 s36, s12, 46
	v_lshl_add_u64 v[74:75], s[36:37], 2, v[4:5]
	s_mul_i32 s36, s12, 47
	v_lshl_add_u64 v[76:77], s[36:37], 2, v[4:5]
	s_mul_i32 s36, s12, 48
	v_lshl_add_u64 v[78:79], s[36:37], 2, v[4:5]
	s_mul_i32 s36, s12, 49
	global_load_dword v64, v[6:7], off nt
	global_load_dword v65, v[66:67], off nt
	s_nop 0
	global_load_dword v66, v[68:69], off nt
	global_load_dword v67, v[70:71], off nt
	s_nop 0
	global_load_dword v68, v[72:73], off nt
	global_load_dword v69, v[74:75], off nt
	global_load_dword v70, v[76:77], off nt
	global_load_dword v71, v[78:79], off nt
	v_lshl_add_u64 v[6:7], s[36:37], 2, v[4:5]
	s_mul_i32 s36, s12, 50
	v_lshl_add_u64 v[74:75], s[36:37], 2, v[4:5]
	s_mul_i32 s36, s12, 51
	v_lshl_add_u64 v[76:77], s[36:37], 2, v[4:5]
	s_mul_i32 s36, s12, 52
	v_lshl_add_u64 v[78:79], s[36:37], 2, v[4:5]
	s_mul_i32 s36, s12, 53
	v_lshl_add_u64 v[80:81], s[36:37], 2, v[4:5]
	s_mul_i32 s36, s12, 54
	v_lshl_add_u64 v[82:83], s[36:37], 2, v[4:5]
	s_mul_i32 s36, s12, 55
	v_lshl_add_u64 v[84:85], s[36:37], 2, v[4:5]
	s_mul_i32 s36, s12, 56
	v_lshl_add_u64 v[86:87], s[36:37], 2, v[4:5]
	s_mul_i32 s36, s12, 57
	global_load_dword v72, v[6:7], off nt
	global_load_dword v73, v[74:75], off nt
	s_nop 0
	global_load_dword v74, v[76:77], off nt
	global_load_dword v75, v[78:79], off nt
	s_nop 0
	global_load_dword v76, v[80:81], off nt
	global_load_dword v77, v[82:83], off nt
	global_load_dword v78, v[84:85], off nt
	global_load_dword v79, v[86:87], off nt
	v_lshl_add_u64 v[6:7], s[36:37], 2, v[4:5]
	s_mul_i32 s36, s12, 58
	v_lshl_add_u64 v[82:83], s[36:37], 2, v[4:5]
	s_mul_i32 s36, s12, 59
	v_lshl_add_u64 v[84:85], s[36:37], 2, v[4:5]
	s_mul_i32 s36, s12, 60
	v_lshl_add_u64 v[86:87], s[36:37], 2, v[4:5]
	s_mul_i32 s36, s12, 61
	v_lshl_add_u64 v[88:89], s[36:37], 2, v[4:5]
	s_mul_i32 s36, s12, 62
	s_mul_i32 s12, s12, 63
	s_waitcnt lgkmcnt(14)
	v_lshl_add_u64 v[90:91], s[36:37], 2, v[4:5]
	v_lshl_add_u64 v[4:5], s[12:13], 2, v[4:5]
	global_load_dword v80, v32, s[26:27]
	global_load_dword v81, v[6:7], off nt
	s_nop 0
	global_load_dword v82, v[82:83], off nt
	s_nop 0
	global_load_dword v83, v[84:85], off nt
	s_nop 0
	global_load_dword v84, v[86:87], off nt
	global_load_dword v85, v[88:89], off nt
	s_nop 0
	global_load_dword v86, v[90:91], off nt
	global_load_dword v87, v[4:5], off nt
